# MLA LDS staging writes straight-line (K part 0 and V unmasked, one wave-uniform mask for K part 1)
# speedup vs baseline: 1.0076x; 1.0076x over previous
; #define LAS __attribute__((address_space(3)))
; #define LBAR() asm volatile("s_waitcnt lgkmcnt(0)\n\ts_barrier" ::: "memory")
; template <int NT, int DQK, int DV, int MODE, int PD, class Src> ...
;     ...
;     for (int u = 0; u < PD; ++u) {
;       const int kc = kcb + u;
;       if (kc < kc1) {
;         LAS unsigned char* buf = lds + ((kc - kc0) & 1) * BUF;
; #pragma unroll
;         for (int rr = 0; rr < NKR; ++rr) { const int idx = tid + 512 * rr; if (idx < NKI) { const int row = idx / KCH, ch = idx % KCH; *(LAS u32x4*)(buf + row * KSTR + ch * 16) = kreg[u][rr]; } }
; #pragma unroll
;         for (int rr = 0; rr < NVR; ++rr) { const int idx = tid + 512 * rr; if (idx < NVI) { const int row = idx / VCH, ch = idx % VCH; *(LAS u32x4*)(buf + KB + row * VSTR + ch * 16) = vreg[u][rr]; } }
;         if (kc + PD < kc1) ABL_LOAD(u, kc + PD);
;         LBAR();
.LBB0_758:
	s_bitcmp1_b32 s72, 0
	s_cselect_b32 s8, 0x5c00, 0
	s_add_i32 s71, s8, 0
	v_add3_u32 v1, s71, v242, v243
	s_waitcnt vmcnt(0)
	ds_write_b128 v1, v[26:29]
	v_add3_u32 v1, s71, v195, v203
	ds_write_b128 v1, v[34:37] offset:13312
	s_and_saveexec_b64 s[20:21], s[12:13]
	s_cbranch_execz .LBB0_762
	v_add3_u32 v1, s71, v244, v245
	ds_write_b128 v1, v[30:33]

; #define LAS __attribute__((address_space(3)))
; __device__ __forceinline__ float ex2(float x) { return __builtin_amdgcn_exp2f(x); }
;   __device__ __forceinline__ bf16_t* W() const { return (bf16_t*)(ws + WS_W); }
; template <int NT, int NKK, int NDT, int MODE, bool MASK> ...
;     ...
;   for (int j = 0; j < NT; ++j) {
;     float mx = -INFINITY;
; #pragma unroll
;     for (int t = 0; t < 4; ++t)
; #pragma unroll
;       for (int i = 0; i < 4; ++i) {
;         if (MASK) { const int kp = kpos0 + 16 * t + 4 * lg + i; if (!mask_ok<MODE>(tq[j], kp, W)) s[j][t][i] = -INFINITY; }
;         mx = fmaxf(mx, s[j][t][i]);
;       }
;     mx = max_x16_x32(mx);
;     if (__any(mx > m[j] + 8.0f / c)) {
;       const float mnew = fmaxf(m[j], mx);
;       const float ms2 = (mnew == -INFINITY) ? 0.f : mnew;
;       const float alpha = ex2((m[j] - ms2) * c);
;       m[j] = mnew; l[j] *= alpha;
; #pragma unroll
;       for (int dt = 0; dt < NDT; ++dt) o[j][dt] *= alpha;
;     }
; template <int NT, int DQK, int DV, int MODE, int PD, class Src> ...
;     ...
;         for (int rr = 0; rr < NKR; ++rr) { const int idx = tid + 512 * rr; if (idx < NKI) { const int row = idx / KCH, ch = idx % KCH; *(LAS u32x4*)(buf + row * KSTR + ch * 16) = kreg[u][rr]; } }
; #pragma unroll
;         for (int rr = 0; rr < NVR; ++rr) { const int idx = tid + 512 * rr; if (idx < NVI) { const int row = idx / VCH, ch = idx % VCH; *(LAS u32x4*)(buf + KB + row * VSTR + ch * 16) = vreg[u][rr]; } }
.LBB0_772:
	v_mul_f32_e32 v186, 0x3e16c740, v187
	v_cmp_neq_f32_e32 vcc, s81, v187
	s_nop 1
	v_cndmask_b32_e32 v186, 0, v186, vcc
	v_fma_f32 v182, v182, s88, -v186
	v_exp_f32_e32 v205, v182
	v_fma_f32 v182, v183, s88, -v186
	v_exp_f32_e32 v207, v182
	v_fma_f32 v182, v184, s88, -v186
	v_exp_f32_e32 v246, v182
	v_fma_f32 v182, v185, s88, -v186
	v_exp_f32_e32 v247, v182
	v_fma_f32 v178, v178, s88, -v186
	v_exp_f32_e32 v248, v178
	v_fma_f32 v178, v179, s88, -v186
	v_add_f32_e32 v182, v207, v205
	v_exp_f32_e32 v249, v178
	v_fma_f32 v178, v180, s88, -v186
	v_add_f32_e32 v182, v246, v182
	v_exp_f32_e32 v250, v178
	v_fma_f32 v178, v181, s88, -v186
	v_add_f32_e32 v182, v247, v182
	v_exp_f32_e32 v251, v178
	v_fma_f32 v174, v174, s88, -v186
	v_add_f32_e32 v178, v248, v182
	v_exp_f32_e32 v252, v174
	v_fma_f32 v174, v175, s88, -v186
	v_add_f32_e32 v178, v249, v178
	v_exp_f32_e32 v231, v174
	v_fma_f32 v174, v176, s88, -v186
	v_add_f32_e32 v178, v250, v178
	v_exp_f32_e32 v229, v174
	v_fma_f32 v174, v177, s88, -v186
	v_add_f32_e32 v178, v251, v178
	v_exp_f32_e32 v230, v174
	v_fma_f32 v170, v170, s88, -v186
	v_add_f32_e32 v174, v252, v178
	v_exp_f32_e32 v232, v170
	v_fma_f32 v170, v171, s88, -v186
	v_add_f32_e32 v174, v231, v174
	v_exp_f32_e32 v228, v170
	v_fma_f32 v170, v172, s88, -v186
	v_add_f32_e32 v174, v229, v174
	v_exp_f32_e32 v196, v170
	v_fma_f32 v170, v173, s88, -v186
	v_add_f32_e32 v174, v230, v174
	v_exp_f32_e32 v173, v170
	v_add_f32_e32 v170, v232, v174
	v_add_f32_e32 v170, v228, v170
	v_add_f32_e32 v170, v196, v170
	v_add_f32_e32 v170, v173, v170
	v_add_f32_e32 v224, v224, v170
	v_max3_f32 v170, v189, v150, v151
	v_max3_f32 v170, v170, v152, v153
	v_max3_f32 v170, v170, v142, v143
	v_max3_f32 v170, v170, v144, v145
	v_mov_b32_e32 v171, v170
	s_nop 1
	v_permlane16_swap_b32_e32 v170, v171
	v_max_f32_e32 v170, v170, v171
	v_mov_b32_e32 v171, v170
	s_nop 1
	v_permlane32_swap_b32_e32 v170, v171
	v_max_f32_e32 v170, v170, v171
	v_add_f32_e32 v171, 0x4259535f, v223
	v_cmp_gt_f32_e32 vcc, v170, v171
	s_cbranch_vccz .LBB0_786
	v_max_f32_e32 v170, v170, v170
	v_max_f32_e32 v171, v223, v223
	v_max_f32_e32 v197, v171, v170
	v_cmp_neq_f32_e32 vcc, s81, v197
	s_nop 1
	v_cndmask_b32_e32 v170, 0, v197, vcc
	v_sub_f32_e32 v170, v223, v170
	v_mul_f32_e32 v170, 0x3e16c740, v170
	v_exp_f32_e32 v170, v170
	v_mov_b32_e32 v223, v197
	v_mul_f32_e32 v225, v225, v170
	v_pk_mul_f32 v[84:85], v[84:85], v[170:171] op_sel_hi:[1,0]
	v_pk_mul_f32 v[82:83], v[82:83], v[170:171] op_sel_hi:[1,0]
	v_pk_mul_f32 v[80:81], v[80:81], v[170:171] op_sel_hi:[1,0]
	v_pk_mul_f32 v[78:79], v[78:79], v[170:171] op_sel_hi:[1,0]
	v_pk_mul_f32 v[72:73], v[72:73], v[170:171] op_sel_hi:[1,0]
	v_pk_mul_f32 v[70:71], v[70:71], v[170:171] op_sel_hi:[1,0]
	v_pk_mul_f32 v[64:65], v[64:65], v[170:171] op_sel_hi:[1,0]
	v_pk_mul_f32 v[62:63], v[62:63], v[170:171] op_sel_hi:[1,0]
	s_branch .LBB0_787
.LBB0_776:
	s_and_saveexec_b64 s[22:23], s[16:17]
	s_xor_b64 s[22:23], exec, s[22:23]
	s_cbranch_execz .LBB0_778
	v_lshl_add_u64 v[26:27], v[208:209], 0, s[100:101]

; #define LAS __attribute__((address_space(3)))
; #define LBAR() asm volatile("s_waitcnt lgkmcnt(0)\n\ts_barrier" ::: "memory")
; template <int NT, int DQK, int DV, int MODE, int PD, class Src> ...
;     ...
;     for (int u = 0; u < PD; ++u) {
;       const int kc = kcb + u;
;       if (kc < kc1) {
;         LAS unsigned char* buf = lds + ((kc - kc0) & 1) * BUF;
; #pragma unroll
;         for (int rr = 0; rr < NKR; ++rr) { const int idx = tid + 512 * rr; if (idx < NKI) { const int row = idx / KCH, ch = idx % KCH; *(LAS u32x4*)(buf + row * KSTR + ch * 16) = kreg[u][rr]; } }
; #pragma unroll
;         for (int rr = 0; rr < NVR; ++rr) { const int idx = tid + 512 * rr; if (idx < NVI) { const int row = idx / VCH, ch = idx % VCH; *(LAS u32x4*)(buf + KB + row * VSTR + ch * 16) = vreg[u][rr]; } }
;         if (kc + PD < kc1) ABL_LOAD(u, kc + PD);
;         LBAR();
.LBB0_797:
	s_add_i32 s8, s72, 1
	s_cmp_ge_u32 s8, s65
	s_cbranch_scc1 .LBB0_837
	s_bitcmp1_b32 s8, 0
	s_cselect_b32 s8, 0x5c00, 0
	s_add_i32 s73, s8, 0
	v_add3_u32 v1, s73, v242, v243
	s_waitcnt vmcnt(0)
	ds_write_b128 v1, v[38:41]
	v_add3_u32 v1, s73, v195, v203
	ds_write_b128 v1, v[42:45] offset:13312
	s_and_saveexec_b64 s[20:21], s[12:13]
	s_cbranch_execz .Lpbw_1
	v_add3_u32 v1, s73, v244, v245
	ds_write_b128 v1, v[46:49]
.Lpbw_1:
	s_or_b64 exec, exec, s[20:21]
	s_cmp_ge_u32 s72, s64
	s_cbranch_scc1 .LBB0_810

; #define LAS __attribute__((address_space(3)))
; #define LBAR() asm volatile("s_waitcnt lgkmcnt(0)\n\ts_barrier" ::: "memory")
; template <int NT, int DQK, int DV, int MODE, int PD, class Src> ...
;     ...
;     for (int u = 0; u < PD; ++u) {
;       const int kc = kcb + u;
;       if (kc < kc1) {
;         LAS unsigned char* buf = lds + ((kc - kc0) & 1) * BUF;
; #pragma unroll
;         for (int rr = 0; rr < NKR; ++rr) { const int idx = tid + 512 * rr; if (idx < NKI) { const int row = idx / KCH, ch = idx % KCH; *(LAS u32x4*)(buf + row * KSTR + ch * 16) = kreg[u][rr]; } }
; #pragma unroll
;         for (int rr = 0; rr < NVR; ++rr) { const int idx = tid + 512 * rr; if (idx < NVI) { const int row = idx / VCH, ch = idx % VCH; *(LAS u32x4*)(buf + KB + row * VSTR + ch * 16) = vreg[u][rr]; } }
;         if (kc + PD < kc1) ABL_LOAD(u, kc + PD);
;         LBAR();
.LBB0_837:
	s_add_i32 s8, s72, 2
	s_cmp_ge_u32 s8, s65
	s_cbranch_scc1 .LBB0_877
	v_add3_u32 v1, s71, v242, v243
	s_waitcnt vmcnt(0)
	ds_write_b128 v1, v[50:53]
	v_add3_u32 v1, s71, v195, v203
	ds_write_b128 v1, v[54:57] offset:13312
	s_and_saveexec_b64 s[20:21], s[12:13]
	s_cbranch_execz .Lpbw_2
	v_add3_u32 v1, s71, v244, v245
	ds_write_b128 v1, v[58:61]
.Lpbw_2:
	s_or_b64 exec, exec, s[20:21]
	s_add_i32 s72, s72, 5
	s_cmp_ge_u32 s72, s65
	s_cbranch_scc1 .LBB0_850

; #define LAS __attribute__((address_space(3)))
; #define LBAR() asm volatile("s_waitcnt lgkmcnt(0)\n\ts_barrier" ::: "memory")
; template <int NT, int DQK, int DV, int MODE, int PD, class Src> ...
;     ...
;     for (int u = 0; u < PD; ++u) {
;       const int kc = kcb + u;
;       if (kc < kc1) {
;         LAS unsigned char* buf = lds + ((kc - kc0) & 1) * BUF;
; #pragma unroll
;         for (int rr = 0; rr < NKR; ++rr) { const int idx = tid + 512 * rr; if (idx < NKI) { const int row = idx / KCH, ch = idx % KCH; *(LAS u32x4*)(buf + row * KSTR + ch * 16) = kreg[u][rr]; } }
; #pragma unroll
;         for (int rr = 0; rr < NVR; ++rr) { const int idx = tid + 512 * rr; if (idx < NVI) { const int row = idx / VCH, ch = idx % VCH; *(LAS u32x4*)(buf + KB + row * VSTR + ch * 16) = vreg[u][rr]; } }
;         if (kc + PD < kc1) ABL_LOAD(u, kc + PD);
;         LBAR();
.LBB0_931:
	s_bitcmp1_b32 s58, 0
	s_cselect_b32 s8, 0x5c00, 0
	s_add_i32 s45, s8, 0
	v_add3_u32 v1, s45, v242, v243
	s_waitcnt vmcnt(0)
	ds_write_b128 v1, v[26:29]
	v_add3_u32 v1, s45, v195, v203
	ds_write_b128 v1, v[34:37] offset:13312
	s_and_saveexec_b64 s[20:21], s[12:13]
	s_cbranch_execz .LBB0_935
	v_add3_u32 v1, s45, v244, v245
	ds_write_b128 v1, v[30:33]

; #define LAS __attribute__((address_space(3)))
; __device__ __forceinline__ float ex2(float x) { return __builtin_amdgcn_exp2f(x); }
;   __device__ __forceinline__ bf16_t* W() const { return (bf16_t*)(ws + WS_W); }
; template <int NT, int NKK, int NDT, int MODE, bool MASK> ...
;     ...
;   for (int j = 0; j < NT; ++j) {
;     float mx = -INFINITY;
; #pragma unroll
;     for (int t = 0; t < 4; ++t)
; #pragma unroll
;       for (int i = 0; i < 4; ++i) {
;         if (MASK) { const int kp = kpos0 + 16 * t + 4 * lg + i; if (!mask_ok<MODE>(tq[j], kp, W)) s[j][t][i] = -INFINITY; }
;         mx = fmaxf(mx, s[j][t][i]);
;       }
;     mx = max_x16_x32(mx);
;     if (__any(mx > m[j] + 8.0f / c)) {
;       const float mnew = fmaxf(m[j], mx);
;       const float ms2 = (mnew == -INFINITY) ? 0.f : mnew;
;       const float alpha = ex2((m[j] - ms2) * c);
;       m[j] = mnew; l[j] *= alpha;
; #pragma unroll
;       for (int dt = 0; dt < NDT; ++dt) o[j][dt] *= alpha;
;     }
; template <int NT, int DQK, int DV, int MODE, int PD, class Src> ...
;     ...
;         for (int rr = 0; rr < NKR; ++rr) { const int idx = tid + 512 * rr; if (idx < NKI) { const int row = idx / KCH, ch = idx % KCH; *(LAS u32x4*)(buf + row * KSTR + ch * 16) = kreg[u][rr]; } }
; #pragma unroll
;         for (int rr = 0; rr < NVR; ++rr) { const int idx = tid + 512 * rr; if (idx < NVI) { const int row = idx / VCH, ch = idx % VCH; *(LAS u32x4*)(buf + KB + row * VSTR + ch * 16) = vreg[u][rr]; } }
.LBB0_945:
	v_mul_f32_e32 v186, 0x3e16c740, v187
	v_cmp_neq_f32_e32 vcc, s81, v187
	s_nop 1
	v_cndmask_b32_e32 v186, 0, v186, vcc
	v_fma_f32 v182, v182, s88, -v186
	v_exp_f32_e32 v205, v182
	v_fma_f32 v182, v183, s88, -v186
	v_exp_f32_e32 v207, v182
	v_fma_f32 v182, v184, s88, -v186
	v_exp_f32_e32 v246, v182
	v_fma_f32 v182, v185, s88, -v186
	v_exp_f32_e32 v247, v182
	v_fma_f32 v178, v178, s88, -v186
	v_exp_f32_e32 v248, v178
	v_fma_f32 v178, v179, s88, -v186
	v_add_f32_e32 v182, v207, v205
	v_exp_f32_e32 v249, v178
	v_fma_f32 v178, v180, s88, -v186
	v_add_f32_e32 v182, v246, v182
	v_exp_f32_e32 v250, v178
	v_fma_f32 v178, v181, s88, -v186
	v_add_f32_e32 v182, v247, v182
	v_exp_f32_e32 v251, v178
	v_fma_f32 v174, v174, s88, -v186
	v_add_f32_e32 v178, v248, v182
	v_exp_f32_e32 v252, v174
	v_fma_f32 v174, v175, s88, -v186
	v_add_f32_e32 v178, v249, v178
	v_exp_f32_e32 v231, v174
	v_fma_f32 v174, v176, s88, -v186
	v_add_f32_e32 v178, v250, v178
	v_exp_f32_e32 v229, v174
	v_fma_f32 v174, v177, s88, -v186
	v_add_f32_e32 v178, v251, v178
	v_exp_f32_e32 v230, v174
	v_fma_f32 v170, v170, s88, -v186
	v_add_f32_e32 v174, v252, v178
	v_exp_f32_e32 v232, v170
	v_fma_f32 v170, v171, s88, -v186
	v_add_f32_e32 v174, v231, v174
	v_exp_f32_e32 v228, v170
	v_fma_f32 v170, v172, s88, -v186
	v_add_f32_e32 v174, v229, v174
	v_exp_f32_e32 v196, v170
	v_fma_f32 v170, v173, s88, -v186
	v_add_f32_e32 v174, v230, v174
	v_exp_f32_e32 v173, v170
	v_add_f32_e32 v170, v232, v174
	v_add_f32_e32 v170, v228, v170
	v_add_f32_e32 v170, v196, v170
	v_add_f32_e32 v170, v173, v170
	v_add_f32_e32 v224, v224, v170
	v_max3_f32 v170, v189, v150, v151
	v_max3_f32 v170, v170, v152, v153
	v_max3_f32 v170, v170, v142, v143
	v_max3_f32 v170, v170, v144, v145
	v_mov_b32_e32 v171, v170
	s_nop 1
	v_permlane16_swap_b32_e32 v170, v171
	v_max_f32_e32 v170, v170, v171
	v_mov_b32_e32 v171, v170
	s_nop 1
	v_permlane32_swap_b32_e32 v170, v171
	v_max_f32_e32 v170, v170, v171
	v_add_f32_e32 v171, 0x4259535f, v223
	v_cmp_gt_f32_e32 vcc, v170, v171
	s_cbranch_vccz .LBB0_959
	v_max_f32_e32 v170, v170, v170
	v_max_f32_e32 v171, v223, v223
	v_max_f32_e32 v197, v171, v170
	v_cmp_neq_f32_e32 vcc, s81, v197
	s_nop 1
	v_cndmask_b32_e32 v170, 0, v197, vcc
	v_sub_f32_e32 v170, v223, v170
	v_mul_f32_e32 v170, 0x3e16c740, v170
	v_exp_f32_e32 v170, v170
	v_mov_b32_e32 v223, v197
	v_mul_f32_e32 v225, v225, v170
	v_pk_mul_f32 v[84:85], v[84:85], v[170:171] op_sel_hi:[1,0]
	v_pk_mul_f32 v[82:83], v[82:83], v[170:171] op_sel_hi:[1,0]
	v_pk_mul_f32 v[80:81], v[80:81], v[170:171] op_sel_hi:[1,0]
	v_pk_mul_f32 v[78:79], v[78:79], v[170:171] op_sel_hi:[1,0]
	v_pk_mul_f32 v[72:73], v[72:73], v[170:171] op_sel_hi:[1,0]
	v_pk_mul_f32 v[70:71], v[70:71], v[170:171] op_sel_hi:[1,0]
	v_pk_mul_f32 v[64:65], v[64:65], v[170:171] op_sel_hi:[1,0]
	v_pk_mul_f32 v[62:63], v[62:63], v[170:171] op_sel_hi:[1,0]
	s_branch .LBB0_960
.LBB0_949:
	s_and_saveexec_b64 s[22:23], s[16:17]
	s_xor_b64 s[22:23], exec, s[22:23]
	s_cbranch_execz .LBB0_951
	v_lshl_add_u64 v[26:27], v[208:209], 0, s[100:101]

; #define LAS __attribute__((address_space(3)))
; #define LBAR() asm volatile("s_waitcnt lgkmcnt(0)\n\ts_barrier" ::: "memory")
; template <int NT, int DQK, int DV, int MODE, int PD, class Src> ...
;     ...
;     for (int u = 0; u < PD; ++u) {
;       const int kc = kcb + u;
;       if (kc < kc1) {
;         LAS unsigned char* buf = lds + ((kc - kc0) & 1) * BUF;
; #pragma unroll
;         for (int rr = 0; rr < NKR; ++rr) { const int idx = tid + 512 * rr; if (idx < NKI) { const int row = idx / KCH, ch = idx % KCH; *(LAS u32x4*)(buf + row * KSTR + ch * 16) = kreg[u][rr]; } }
; #pragma unroll
;         for (int rr = 0; rr < NVR; ++rr) { const int idx = tid + 512 * rr; if (idx < NVI) { const int row = idx / VCH, ch = idx % VCH; *(LAS u32x4*)(buf + KB + row * VSTR + ch * 16) = vreg[u][rr]; } }
;         if (kc + PD < kc1) ABL_LOAD(u, kc + PD);
;         LBAR();
.LBB0_970:
	s_add_i32 s8, s58, 1
	s_cmp_ge_u32 s8, s35
	s_cbranch_scc1 .LBB0_1010
	s_bitcmp1_b32 s8, 0
	s_cselect_b32 s8, 0x5c00, 0
	s_add_i32 s59, s8, 0
	v_add3_u32 v1, s59, v242, v243
	s_waitcnt vmcnt(0)
	ds_write_b128 v1, v[38:41]
	v_add3_u32 v1, s59, v195, v203
	ds_write_b128 v1, v[42:45] offset:13312
	s_and_saveexec_b64 s[20:21], s[12:13]
	s_cbranch_execz .Lpbw_4
	v_add3_u32 v1, s59, v244, v245
	ds_write_b128 v1, v[46:49]
.Lpbw_4:
	s_or_b64 exec, exec, s[20:21]
	s_cmp_ge_u32 s58, s34
	s_cbranch_scc1 .LBB0_983

; #define LAS __attribute__((address_space(3)))
; #define LBAR() asm volatile("s_waitcnt lgkmcnt(0)\n\ts_barrier" ::: "memory")
; template <int NT, int DQK, int DV, int MODE, int PD, class Src> ...
;     ...
;     for (int u = 0; u < PD; ++u) {
;       const int kc = kcb + u;
;       if (kc < kc1) {
;         LAS unsigned char* buf = lds + ((kc - kc0) & 1) * BUF;
; #pragma unroll
;         for (int rr = 0; rr < NKR; ++rr) { const int idx = tid + 512 * rr; if (idx < NKI) { const int row = idx / KCH, ch = idx % KCH; *(LAS u32x4*)(buf + row * KSTR + ch * 16) = kreg[u][rr]; } }
; #pragma unroll
;         for (int rr = 0; rr < NVR; ++rr) { const int idx = tid + 512 * rr; if (idx < NVI) { const int row = idx / VCH, ch = idx % VCH; *(LAS u32x4*)(buf + KB + row * VSTR + ch * 16) = vreg[u][rr]; } }
;         if (kc + PD < kc1) ABL_LOAD(u, kc + PD);
;         LBAR();
.LBB0_1010:
	s_add_i32 s8, s58, 2
	s_cmp_ge_u32 s8, s35
	s_cbranch_scc1 .LBB0_1050
	v_add3_u32 v1, s45, v242, v243
	s_waitcnt vmcnt(0)
	ds_write_b128 v1, v[50:53]
	v_add3_u32 v1, s45, v195, v203
	ds_write_b128 v1, v[54:57] offset:13312
	s_and_saveexec_b64 s[20:21], s[12:13]
	s_cbranch_execz .Lpbw_5
	v_add3_u32 v1, s45, v244, v245
	ds_write_b128 v1, v[58:61]
.Lpbw_5:
	s_or_b64 exec, exec, s[20:21]
	s_add_i32 s58, s58, 5
	s_cmp_ge_u32 s58, s35
	s_cbranch_scc1 .LBB0_1023
